# Z1: accumulator clears before each GEMM unit's K-loop use 64 v_mov_b64 instead of 128 v_mov_b32 (ff1, out/ff2 and w_in unit loops); on top of X1
# speedup vs baseline: 1.0079x; 1.0079x over previous
.LBB0_233:
	s_ashr_i32 s31, s30, 31
	s_lshl_b64 s[26:27], s[30:31], 19
	s_add_u32 s34, s18, s26
	s_addc_u32 s35, s62, s27
	s_and_b64 s[26:27], s[36:37], exec
	s_cselect_b32 s31, s35, s39
	s_cselect_b32 s80, s34, s38
	s_ashr_i32 s15, s14, 31
	s_lshl_b64 s[26:27], s[14:15], 19
	s_add_u32 s98, s9, s26
	s_addc_u32 s99, s63, s27
	s_and_b64 s[26:27], s[36:37], exec
	s_cselect_b32 s15, s99, s7
	s_cselect_b32 s86, s98, s6
	s_add_u32 s87, s6, 0x100
	s_addc_u32 s88, s7, 0
	s_add_u32 s6, s38, 0x40080
	v_mov_b64_e32 v[0:1], 0
	s_addc_u32 s7, s39, 0
	s_mov_b32 s89, -2
	v_mov_b64_e32 v[2:3], 0
	v_mov_b64_e32 v[4:5], 0
	v_mov_b64_e32 v[6:7], 0
	v_mov_b64_e32 v[16:17], 0
	v_mov_b64_e32 v[18:19], 0
	v_mov_b64_e32 v[20:21], 0
	v_mov_b64_e32 v[22:23], 0
	v_mov_b64_e32 v[32:33], 0
	v_mov_b64_e32 v[34:35], 0
	v_mov_b64_e32 v[36:37], 0
	v_mov_b64_e32 v[38:39], 0
	v_mov_b64_e32 v[48:49], 0
	v_mov_b64_e32 v[50:51], 0
	v_mov_b64_e32 v[52:53], 0
	v_mov_b64_e32 v[54:55], 0
	v_mov_b64_e32 v[8:9], 0
	v_mov_b64_e32 v[10:11], 0
	v_mov_b64_e32 v[12:13], 0
	v_mov_b64_e32 v[14:15], 0
	v_mov_b64_e32 v[24:25], 0
	v_mov_b64_e32 v[26:27], 0
	v_mov_b64_e32 v[28:29], 0
	v_mov_b64_e32 v[30:31], 0
	v_mov_b64_e32 v[40:41], 0
	v_mov_b64_e32 v[42:43], 0
	v_mov_b64_e32 v[44:45], 0
	v_mov_b64_e32 v[46:47], 0
	v_mov_b64_e32 v[56:57], 0
	v_mov_b64_e32 v[58:59], 0
	v_mov_b64_e32 v[60:61], 0
	v_mov_b64_e32 v[62:63], 0
	v_mov_b64_e32 v[64:65], 0
	v_mov_b64_e32 v[66:67], 0
	v_mov_b64_e32 v[68:69], 0
	v_mov_b64_e32 v[70:71], 0
	v_mov_b64_e32 v[82:83], 0
	v_mov_b64_e32 v[84:85], 0
	v_mov_b64_e32 v[86:87], 0
	v_mov_b64_e32 v[88:89], 0
	v_mov_b64_e32 v[98:99], 0
	v_mov_b64_e32 v[100:101], 0
	v_mov_b64_e32 v[102:103], 0
	v_mov_b64_e32 v[104:105], 0
	v_mov_b64_e32 v[114:115], 0
	v_mov_b64_e32 v[116:117], 0
	v_mov_b64_e32 v[118:119], 0
	v_mov_b64_e32 v[120:121], 0
	v_mov_b64_e32 v[72:73], 0
	v_mov_b64_e32 v[74:75], 0
	v_mov_b64_e32 v[76:77], 0
	v_mov_b64_e32 v[78:79], 0
	v_mov_b64_e32 v[90:91], 0
	v_mov_b64_e32 v[92:93], 0
	v_mov_b64_e32 v[94:95], 0
	v_mov_b64_e32 v[96:97], 0
	v_mov_b64_e32 v[106:107], 0
	v_mov_b64_e32 v[108:109], 0
	v_mov_b64_e32 v[110:111], 0
	v_mov_b64_e32 v[112:113], 0
	v_mov_b64_e32 v[122:123], 0
	v_mov_b64_e32 v[124:125], 0
	v_mov_b64_e32 v[126:127], 0
	v_mov_b64_e32 v[128:129], 0

.LBB0_388:
	s_ashr_i32 s31, s30, 31
	s_lshl_b64 s[26:27], s[30:31], s64
	s_add_u32 s23, s60, s26
	s_addc_u32 s31, s61, s27
	s_and_b64 s[26:27], s[36:37], exec
	s_cselect_b32 s35, s31, s7
	s_cselect_b32 s34, s23, s6
	s_ashr_i32 s23, s22, 31
	s_lshl_b64 s[26:27], s[22:23], s64
	s_add_u32 s23, s9, s26
	s_addc_u32 s31, s62, s27
	s_and_b64 s[26:27], s[36:37], exec
	s_cselect_b32 s39, s31, s1
	s_cselect_b32 s38, s23, s0
	s_add_u32 s23, s0, 0x100
	s_addc_u32 s31, s1, 0
	s_add_u32 s0, s6, 0x80
	v_mov_b64_e32 v[0:1], 0
	s_addc_u32 s1, s7, 0
	s_mov_b32 s6, 0
	v_mov_b64_e32 v[2:3], 0
	v_mov_b64_e32 v[4:5], 0
	v_mov_b64_e32 v[6:7], 0
	v_mov_b64_e32 v[12:13], 0
	v_mov_b64_e32 v[14:15], 0
	v_mov_b64_e32 v[20:21], 0
	v_mov_b64_e32 v[22:23], 0
	v_mov_b64_e32 v[28:29], 0
	v_mov_b64_e32 v[30:31], 0
	v_mov_b64_e32 v[36:37], 0
	v_mov_b64_e32 v[38:39], 0
	v_mov_b64_e32 v[44:45], 0
	v_mov_b64_e32 v[46:47], 0
	v_mov_b64_e32 v[52:53], 0
	v_mov_b64_e32 v[54:55], 0
	v_mov_b64_e32 v[8:9], 0
	v_mov_b64_e32 v[10:11], 0
	v_mov_b64_e32 v[16:17], 0
	v_mov_b64_e32 v[18:19], 0
	v_mov_b64_e32 v[24:25], 0
	v_mov_b64_e32 v[26:27], 0
	v_mov_b64_e32 v[32:33], 0
	v_mov_b64_e32 v[34:35], 0
	v_mov_b64_e32 v[40:41], 0
	v_mov_b64_e32 v[42:43], 0
	v_mov_b64_e32 v[48:49], 0
	v_mov_b64_e32 v[50:51], 0
	v_mov_b64_e32 v[56:57], 0
	v_mov_b64_e32 v[58:59], 0
	v_mov_b64_e32 v[60:61], 0
	v_mov_b64_e32 v[62:63], 0
	v_mov_b64_e32 v[64:65], 0
	v_mov_b64_e32 v[66:67], 0
	v_mov_b64_e32 v[68:69], 0
	v_mov_b64_e32 v[70:71], 0
	v_mov_b64_e32 v[76:77], 0
	v_mov_b64_e32 v[78:79], 0
	v_mov_b64_e32 v[86:87], 0
	v_mov_b64_e32 v[88:89], 0
	v_mov_b64_e32 v[94:95], 0
	v_mov_b64_e32 v[96:97], 0
	v_mov_b64_e32 v[102:103], 0
	v_mov_b64_e32 v[104:105], 0
	v_mov_b64_e32 v[110:111], 0
	v_mov_b64_e32 v[112:113], 0
	v_mov_b64_e32 v[118:119], 0
	v_mov_b64_e32 v[120:121], 0
	v_mov_b64_e32 v[72:73], 0
	v_mov_b64_e32 v[74:75], 0
	v_mov_b64_e32 v[82:83], 0
	v_mov_b64_e32 v[84:85], 0
	v_mov_b64_e32 v[90:91], 0
	v_mov_b64_e32 v[92:93], 0
	v_mov_b64_e32 v[98:99], 0
	v_mov_b64_e32 v[100:101], 0
	v_mov_b64_e32 v[106:107], 0
	v_mov_b64_e32 v[108:109], 0
	v_mov_b64_e32 v[114:115], 0
	v_mov_b64_e32 v[116:117], 0
	v_mov_b64_e32 v[122:123], 0
	v_mov_b64_e32 v[124:125], 0
	v_mov_b64_e32 v[126:127], 0
	v_mov_b64_e32 v[128:129], 0

.Lk0_nbdone:
	s_and_b64 s[30:31], s[36:37], exec
	s_cselect_b32 s15, s27, s1
	s_cselect_b32 s81, s26, s0
	s_add_u32 s82, s0, 0x100
	s_addc_u32 s83, s1, 0
	s_add_u32 s0, s6, 0x40080
	v_mov_b64_e32 v[0:1], 0
	s_addc_u32 s1, s7, 0
	s_mov_b32 s84, -2
	v_mov_b64_e32 v[2:3], 0
	v_mov_b64_e32 v[4:5], 0
	v_mov_b64_e32 v[6:7], 0
	v_mov_b64_e32 v[12:13], 0
	v_mov_b64_e32 v[14:15], 0
	v_mov_b64_e32 v[20:21], 0
	v_mov_b64_e32 v[22:23], 0
	v_mov_b64_e32 v[28:29], 0
	v_mov_b64_e32 v[30:31], 0
	v_mov_b64_e32 v[36:37], 0
	v_mov_b64_e32 v[38:39], 0
	v_mov_b64_e32 v[44:45], 0
	v_mov_b64_e32 v[46:47], 0
	v_mov_b64_e32 v[52:53], 0
	v_mov_b64_e32 v[54:55], 0
	v_mov_b64_e32 v[8:9], 0
	v_mov_b64_e32 v[10:11], 0
	v_mov_b64_e32 v[16:17], 0
	v_mov_b64_e32 v[18:19], 0
	v_mov_b64_e32 v[24:25], 0
	v_mov_b64_e32 v[26:27], 0
	v_mov_b64_e32 v[32:33], 0
	v_mov_b64_e32 v[34:35], 0
	v_mov_b64_e32 v[40:41], 0
	v_mov_b64_e32 v[42:43], 0
	v_mov_b64_e32 v[48:49], 0
	v_mov_b64_e32 v[50:51], 0
	v_mov_b64_e32 v[56:57], 0
	v_mov_b64_e32 v[58:59], 0
	v_mov_b64_e32 v[60:61], 0
	v_mov_b64_e32 v[62:63], 0
	v_mov_b64_e32 v[64:65], 0
	v_mov_b64_e32 v[66:67], 0
	v_mov_b64_e32 v[68:69], 0
	v_mov_b64_e32 v[70:71], 0
	v_mov_b64_e32 v[76:77], 0
	v_mov_b64_e32 v[78:79], 0
	v_mov_b64_e32 v[86:87], 0
	v_mov_b64_e32 v[88:89], 0
	v_mov_b64_e32 v[94:95], 0
	v_mov_b64_e32 v[96:97], 0
	v_mov_b64_e32 v[102:103], 0
	v_mov_b64_e32 v[104:105], 0
	v_mov_b64_e32 v[110:111], 0
	v_mov_b64_e32 v[112:113], 0
	v_mov_b64_e32 v[118:119], 0
	v_mov_b64_e32 v[120:121], 0
	v_mov_b64_e32 v[72:73], 0
	v_mov_b64_e32 v[74:75], 0
	v_mov_b64_e32 v[82:83], 0
	v_mov_b64_e32 v[84:85], 0
	v_mov_b64_e32 v[90:91], 0
	v_mov_b64_e32 v[92:93], 0
	v_mov_b64_e32 v[98:99], 0
	v_mov_b64_e32 v[100:101], 0
	v_mov_b64_e32 v[106:107], 0
	v_mov_b64_e32 v[108:109], 0
	v_mov_b64_e32 v[114:115], 0
	v_mov_b64_e32 v[116:117], 0
	v_mov_b64_e32 v[122:123], 0
	v_mov_b64_e32 v[124:125], 0
	v_mov_b64_e32 v[126:127], 0
	v_mov_b64_e32 v[128:129], 0
